# BMODE=1 B tile swizzle with 3 row bits (separate address register for the +32-row fragment reads): 2-way instead of 4-way write conflicts
# speedup vs baseline: 1.0384x; 1.0009x over previous
.LBB0_252:
	s_add_i32 s0, s6, 0xfffffe20
	s_lshr_b32 s4, s0, 1
	s_bfe_u32 s2, s0, 0x70001
	s_lshl_b32 s0, s0, 5
	s_and_b32 s0, s0, 0x7fffe000
	s_or_b32 s78, s0, s2
	s_waitcnt vmcnt(7)
	v_mov_b32_e32 v36, v208
	s_lshl_b64 s[0:1], s[78:79], 10
	v_readlane_b32 s8, v254, 1
	v_readlane_b32 s9, v254, 2
	v_lshlrev_b32_e32 v1, 7, v36
	s_add_u32 s0, s8, s0
	v_and_b32_e32 v39, 0x2f80, v1
	v_ashrrev_i32_e32 v1, 1, v36
	s_addc_u32 s1, s9, s1
	s_lshl_b32 s2, s2, 15
	v_readlane_b32 s8, v253, 36
	v_and_b32_e32 v37, 31, v36
	v_and_b32_e32 v38, 0xffffffc0, v1
	v_ashrrev_i32_e32 v72, 3, v36
	v_readlane_b32 s9, v253, 37
	s_add_u32 s2, s8, s2
	v_lshrrev_b32_e32 v0, 5, v36
	v_and_b32_e32 v5, 7, v36
	v_or_b32_e32 v1, v38, v37
	v_ashrrev_i32_e32 v73, 31, v72
	s_addc_u32 s3, s9, 0
	v_lshl_add_u32 v100, v1, 7, v214
	v_bitop3_b32 v6, v0, v5, 1 bitop3:0x6c
	v_lshlrev_b64 v[0:1], 8, v[72:73]
	v_lshlrev_b32_e32 v3, 4, v36
	v_lshl_add_u64 v[0:1], s[2:3], 0, v[0:1]
	v_and_b32_e32 v192, 0x70, v3
	v_lshl_add_u64 v[32:33], v[0:1], 0, v[192:193]
	global_load_dwordx4 v[40:43], v[32:33], off
	s_mov_b32 s5, s79
	s_lshl_b64 s[4:5], s[4:5], 16
	v_readlane_b32 s7, v254, 5
	s_add_u32 s4, s7, s4
	v_readlane_b32 s7, v254, 6
	v_ashrrev_i32_e32 v74, 4, v36
	s_addc_u32 s5, s7, s5
	s_lshl_b32 s7, s6, 7
	v_ashrrev_i32_e32 v75, 31, v74
	s_and_b32 s7, s7, 0x80
	v_lshlrev_b32_e32 v2, 3, v36
	v_lshlrev_b64 v[0:1], 9, v[74:75]
	v_add_u32_e32 v7, 0x100, v36
	v_lshl_add_u64 v[0:1], s[4:5], 0, v[0:1]
	s_lshl_b32 s78, s7, 1
	v_and_b32_e32 v73, 0x78, v2
	v_ashrrev_i32_e32 v76, 3, v7
	v_lshl_add_u64 v[0:1], v[0:1], 0, s[78:79]
	v_lshlrev_b32_e32 v2, 1, v73
	v_mov_b32_e32 v3, v193
	v_ashrrev_i32_e32 v77, 31, v76
	v_lshl_add_u64 v[12:13], v[0:1], 0, v[2:3]
	v_lshlrev_b64 v[0:1], 8, v[76:77]
	v_bfe_u32 v4, v36, 5, 1
	v_lshl_add_u64 v[0:1], s[2:3], 0, v[0:1]
	v_lshl_add_u64 v[34:35], v[0:1], 0, v[192:193]
	v_bitop3_b32 v0, v4, v5, 2 bitop3:0x36
	v_lshlrev_b32_e32 v77, 4, v0
	v_bitop3_b32 v0, v4, v5, 4 bitop3:0x36
	v_ashrrev_i32_e32 v78, 4, v7
	v_lshlrev_b32_e32 v101, 4, v0
	v_bitop3_b32 v0, v4, v5, 6 bitop3:0x36
	v_ashrrev_i32_e32 v79, 31, v78
	v_lshlrev_b32_e32 v102, 4, v0
	v_lshlrev_b64 v[0:1], 9, v[78:79]
	v_add_u32_e32 v4, 0x200, v36
	v_lshl_add_u64 v[0:1], s[4:5], 0, v[0:1]
	v_ashrrev_i32_e32 v80, 3, v4
	v_lshl_add_u64 v[0:1], v[0:1], 0, s[78:79]
	v_ashrrev_i32_e32 v81, 31, v80
	v_lshl_add_u64 v[14:15], v[0:1], 0, v[2:3]
	v_lshlrev_b64 v[0:1], 8, v[80:81]
	v_ashrrev_i32_e32 v84, 4, v4
	v_lshl_add_u64 v[0:1], s[2:3], 0, v[0:1]
	v_ashrrev_i32_e32 v85, 31, v84
	v_lshl_add_u64 v[82:83], v[0:1], 0, v[192:193]
	v_lshlrev_b64 v[0:1], 9, v[84:85]
	v_add_u32_e32 v8, 0x300, v36
	v_lshl_add_u64 v[0:1], s[4:5], 0, v[0:1]
	v_ashrrev_i32_e32 v86, 3, v8
	v_lshl_add_u64 v[0:1], v[0:1], 0, s[78:79]
	v_ashrrev_i32_e32 v87, 31, v86
	v_lshl_add_u64 v[24:25], v[0:1], 0, v[2:3]
	v_lshlrev_b64 v[0:1], 8, v[86:87]
	v_ashrrev_i32_e32 v90, 4, v8
	v_lshl_add_u64 v[0:1], s[2:3], 0, v[0:1]
	v_ashrrev_i32_e32 v91, 31, v90
	v_lshl_add_u64 v[88:89], v[0:1], 0, v[192:193]
	v_lshlrev_b64 v[0:1], 9, v[90:91]
	v_lshl_add_u64 v[0:1], s[4:5], 0, v[0:1]
	v_lshl_add_u64 v[0:1], v[0:1], 0, s[78:79]
	v_lshl_add_u64 v[26:27], v[0:1], 0, v[2:3]
	v_xor_b32_e32 v0, v72, v36
	v_lshlrev_b32_e32 v0, 4, v0
	v_and_b32_e32 v0, 0x70, v0
	global_load_dwordx4 v[44:47], v[34:35], off
	global_load_dwordx4 v[48:51], v[12:13], off
	v_lshlrev_b32_e32 v75, 4, v6
	global_load_dwordx4 v[4:7], v[34:35], off offset:128
	global_load_dwordx4 v[52:55], v[14:15], off
	global_load_dwordx4 v[16:19], v[32:33], off offset:128
	global_load_dwordx4 v[56:59], v[82:83], off
	global_load_dwordx4 v[8:11], v[82:83], off offset:128
	v_lshl_or_b32 v134, v72, 7, v0
	global_load_dwordx4 v[60:63], v[88:89], off
	global_load_dwordx4 v[64:67], v[24:25], off
	global_load_dwordx4 v[0:3], v[88:89], off offset:128
	global_load_dwordx4 v[68:71], v[26:27], off
	s_mov_b32 s2, 0x8000
	v_add_co_u32_e32 v92, vcc, s2, v12
	s_movk_i32 s3, 0x50
	s_nop 0
	v_addc_co_u32_e32 v93, vcc, 0, v13, vcc
	v_add_co_u32_e32 v94, vcc, s2, v14
	s_movk_i32 s4, 0x60
	s_nop 0
	v_addc_co_u32_e32 v95, vcc, 0, v15, vcc
	v_add_co_u32_e32 v96, vcc, s2, v24
	global_load_dwordx4 v[28:31], v[92:93], off
	global_load_dwordx4 v[20:23], v[94:95], off
	v_addc_co_u32_e32 v97, vcc, 0, v25, vcc
	v_add_co_u32_e32 v98, vcc, s2, v26
	s_movk_i32 s2, 0x70
	s_nop 0
	v_addc_co_u32_e32 v99, vcc, 0, v27, vcc
	global_load_dwordx4 v[24:27], v[96:97], off
	global_load_dwordx4 v[12:15], v[98:99], off
	s_waitcnt vmcnt(15)
	ds_write_b128 v134, v[40:43]
	v_lshlrev_b32_e32 v40, 1, v74
	v_lshlrev_b32_e32 v41, 7, v73
	v_and_b32_e32 v42, -16, v72
	v_and_b32_e32 v40, 14, v40
	v_add_u32_e32 v43, v41, v42
	v_or_b32_e32 v135, v43, v40
	v_xad_u32 v43, v42, 16, v41
	v_or_b32_e32 v136, v43, v40
	v_xad_u32 v43, v42, 32, v41
	v_or_b32_e32 v137, v43, v40
	v_xad_u32 v43, v42, 48, v41
	v_or_b32_e32 v138, v43, v40
	v_xad_u32 v43, v42, 64, v41
	v_or_b32_e32 v139, v43, v40
	v_xad_u32 v43, v42, s3, v41
	v_or_b32_e32 v140, v43, v40
	v_xad_u32 v43, v42, s4, v41
	v_xad_u32 v42, v42, s2, v41
	v_or_b32_e32 v141, v43, v40
	v_or_b32_e32 v142, v42, v40
	v_xor_b32_e32 v40, v76, v36
	v_lshlrev_b32_e32 v40, 4, v40
	v_and_b32_e32 v40, 0x70, v40
	v_lshl_or_b32 v146, v76, 7, v40
	v_lshlrev_b32_e32 v40, 1, v78
	v_and_b32_e32 v42, -16, v76
	v_and_b32_e32 v40, 14, v40
	v_add_u32_e32 v43, v41, v42
	v_or_b32_e32 v147, v43, v40
	v_xad_u32 v43, v42, 16, v41
	v_or_b32_e32 v148, v43, v40
	v_xad_u32 v43, v42, 32, v41
	v_or_b32_e32 v149, v43, v40
	v_xad_u32 v43, v42, 48, v41
	v_or_b32_e32 v150, v43, v40
	v_xad_u32 v43, v42, 64, v41
	v_or_b32_e32 v151, v43, v40
	v_xad_u32 v43, v42, s3, v41
	v_or_b32_e32 v152, v43, v40
	v_xad_u32 v43, v42, s4, v41
	v_xad_u32 v42, v42, s2, v41
	v_or_b32_e32 v153, v43, v40
	v_or_b32_e32 v154, v42, v40
	v_xor_b32_e32 v40, v80, v36
	v_lshlrev_b32_e32 v40, 4, v40
	v_and_b32_e32 v40, 0x70, v40
	v_lshl_or_b32 v156, v80, 7, v40
	v_lshlrev_b32_e32 v40, 1, v84
	v_and_b32_e32 v42, -16, v80
	v_and_b32_e32 v40, 14, v40
	v_add_u32_e32 v43, v41, v42
	v_or_b32_e32 v157, v43, v40
	v_xad_u32 v43, v42, 16, v41
	v_or_b32_e32 v158, v43, v40
	v_xad_u32 v43, v42, 32, v41
	v_or_b32_e32 v159, v43, v40
	v_xad_u32 v43, v42, 48, v41
	v_or_b32_e32 v160, v43, v40
	v_xad_u32 v43, v42, 64, v41
	v_or_b32_e32 v161, v43, v40
	v_xad_u32 v43, v42, s3, v41
	v_or_b32_e32 v162, v43, v40
	v_xad_u32 v43, v42, s4, v41
	v_xad_u32 v42, v42, s2, v41
	v_or_b32_e32 v163, v43, v40
	v_or_b32_e32 v164, v42, v40
	v_xor_b32_e32 v40, v86, v36
	v_lshlrev_b32_e32 v40, 4, v40
	v_and_b32_e32 v40, 0x70, v40
	v_lshl_or_b32 v165, v86, 7, v40
	v_lshlrev_b32_e32 v40, 1, v90
	v_and_b32_e32 v42, -16, v86
	v_and_b32_e32 v40, 14, v40
	v_add_u32_e32 v43, v41, v42
	v_or_b32_e32 v166, v43, v40
	v_xad_u32 v43, v42, 16, v41
	v_or_b32_e32 v167, v43, v40
	v_xad_u32 v43, v42, 32, v41
	v_or_b32_e32 v168, v43, v40
	v_xad_u32 v43, v42, 48, v41
	v_or_b32_e32 v169, v43, v40
	v_xad_u32 v43, v42, 64, v41
	v_or_b32_e32 v170, v43, v40
	v_xad_u32 v43, v42, s3, v41
	v_or_b32_e32 v171, v43, v40
	v_xad_u32 v43, v42, s4, v41
	v_xad_u32 v41, v42, s2, v41
	v_or_b32_e32 v172, v43, v40
	v_or_b32_e32 v173, v41, v40
	v_and_b32_e32 v175, 7, v208
	v_lshlrev_b32_e32 v175, 4, v175
	v_bfe_u32 v176, v208, 3, 2
	v_lshlrev_b32_e32 v176, 4, v176
	v_xor_b32_e32 v135, v175, v135
	v_xor_b32_e32 v136, v175, v136
	v_xor_b32_e32 v137, v175, v137
	v_xor_b32_e32 v138, v175, v138
	v_xor_b32_e32 v139, v175, v139
	v_xor_b32_e32 v140, v175, v140
	v_xor_b32_e32 v141, v175, v141
	v_xor_b32_e32 v142, v175, v142
	v_xor_b32_e32 v147, v175, v147
	v_xor_b32_e32 v148, v175, v148
	v_xor_b32_e32 v149, v175, v149
	v_xor_b32_e32 v150, v175, v150
	v_xor_b32_e32 v151, v175, v151
	v_xor_b32_e32 v152, v175, v152
	v_xor_b32_e32 v153, v175, v153
	v_xor_b32_e32 v154, v175, v154
	v_xor_b32_e32 v157, v175, v157
	v_xor_b32_e32 v158, v175, v158
	v_xor_b32_e32 v159, v175, v159
	v_xor_b32_e32 v160, v175, v160
	v_xor_b32_e32 v161, v175, v161
	v_xor_b32_e32 v162, v175, v162
	v_xor_b32_e32 v163, v175, v163
	v_xor_b32_e32 v164, v175, v164
	v_xor_b32_e32 v166, v175, v166
	v_xor_b32_e32 v167, v175, v167
	v_xor_b32_e32 v168, v175, v168
	v_xor_b32_e32 v169, v175, v169
	v_xor_b32_e32 v170, v175, v170
	v_xor_b32_e32 v171, v175, v171
	v_xor_b32_e32 v172, v175, v172
	v_xor_b32_e32 v173, v175, v173
	s_waitcnt vmcnt(13)
	ds_write_b16 v135, v48 offset:16384
	ds_write_b16_d16_hi v136, v48 offset:16512
	ds_write_b16 v137, v49 offset:16640
	ds_write_b16_d16_hi v138, v49 offset:16768
	ds_write_b16 v139, v50 offset:16896
	ds_write_b16_d16_hi v140, v50 offset:17024
	ds_write_b16 v141, v51 offset:17152
	ds_write_b16_d16_hi v142, v51 offset:17280
	ds_write_b128 v146, v[44:47]
	s_waitcnt vmcnt(11)
	ds_write_b16 v147, v52 offset:16384
	ds_write_b16_d16_hi v148, v52 offset:16512
	ds_write_b16 v149, v53 offset:16640
	ds_write_b16_d16_hi v150, v53 offset:16768
	ds_write_b16 v151, v54 offset:16896
	ds_write_b16_d16_hi v152, v54 offset:17024
	ds_write_b16 v153, v55 offset:17152
	ds_write_b16_d16_hi v154, v55 offset:17280
	s_waitcnt vmcnt(9)
	ds_write_b128 v156, v[56:59]
	s_waitcnt vmcnt(6)
	ds_write_b16 v157, v64 offset:16384
	ds_write_b16_d16_hi v158, v64 offset:16512
	ds_write_b16 v159, v65 offset:16640
	ds_write_b16_d16_hi v160, v65 offset:16768
	ds_write_b16 v161, v66 offset:16896
	ds_write_b16_d16_hi v162, v66 offset:17024
	ds_write_b16 v163, v67 offset:17152
	ds_write_b16_d16_hi v164, v67 offset:17280
	ds_write_b128 v165, v[60:63]
	s_waitcnt vmcnt(4)
	ds_write_b16 v166, v68 offset:16384
	ds_write_b16_d16_hi v167, v68 offset:16512
	ds_write_b16 v168, v69 offset:16640
	ds_write_b16_d16_hi v169, v69 offset:16768
	ds_write_b16 v170, v70 offset:16896
	ds_write_b16_d16_hi v171, v70 offset:17024
	ds_write_b16 v172, v71 offset:17152
	ds_write_b16_d16_hi v173, v71 offset:17280
	s_waitcnt lgkmcnt(0)
	s_barrier
	global_load_dwordx4 v[40:43], v[32:33], off offset:128
	s_nop 0
	global_load_dwordx4 v[32:35], v[34:35], off offset:128
	s_nop 0
	global_load_dwordx4 v[44:47], v[82:83], off offset:128
	global_load_dwordx4 v[48:51], v[88:89], off offset:128
	global_load_dwordx4 v[52:55], v[92:93], off
	global_load_dwordx4 v[56:59], v[94:95], off
	global_load_dwordx4 v[60:63], v[96:97], off
	global_load_dwordx4 v[64:67], v[98:99], off
	v_or_b32_e32 v132, v100, v75
	v_xor_b32_e32 v132, v176, v132
	v_xor_b32_e32 v177, 64, v132
	v_or_b32_e32 v143, v75, v39
	v_or_b32_e32 v144, v101, v39
	v_or_b32_e32 v145, v100, v77
	v_xor_b32_e32 v145, v176, v145
	v_xor_b32_e32 v180, 64, v145
	v_or_b32_e32 v155, v102, v39
	v_or_b32_e32 v39, v77, v39
	ds_read_b128 v[68:71], v143 offset:0
	ds_read_b128 v[72:75], v143 offset:0x1000
	ds_read_b128 v[76:79], v132 offset:0
	ds_read_b128 v[80:83], v177 offset:0x1000
	v_or_b32_e32 v133, v100, v101
	v_xor_b32_e32 v133, v176, v133
	v_xor_b32_e32 v178, 64, v133
	v_or_b32_e32 v174, v100, v102
	v_xor_b32_e32 v174, v176, v174
	v_xor_b32_e32 v181, 64, v174
	ds_read_b128 v[84:87], v39 offset:0
	ds_read_b128 v[88:91], v39 offset:0x1000
	ds_read_b128 v[92:95], v145 offset:0
	ds_read_b128 v[96:99], v180 offset:0x1000
	ds_read_b128 v[100:103], v144 offset:0
	ds_read_b128 v[104:107], v144 offset:0x1000
	ds_read_b128 v[108:111], v133 offset:0
	ds_read_b128 v[112:115], v178 offset:0x1000
	ds_read_b128 v[116:119], v155 offset:0
	ds_read_b128 v[120:123], v155 offset:0x1000
	ds_read_b128 v[124:127], v174 offset:0
	ds_read_b128 v[128:131], v181 offset:0x1000
	s_waitcnt lgkmcnt(12)
	s_nop 0
	v_mfma_f32_32x32x16_bf16 a[48:63], v[68:71], v[76:79], 0
	s_waitcnt lgkmcnt(8)
	s_waitcnt lgkmcnt(4)
	s_waitcnt lgkmcnt(0)
	ds_write_b128 v134, v[16:19] offset:32768
	s_waitcnt vmcnt(11)
	ds_write_b16 v135, v28 offset:49152
	ds_write_b16_d16_hi v136, v28 offset:49280
	ds_write_b16 v137, v29 offset:49408
	ds_write_b16_d16_hi v138, v29 offset:49536
	ds_write_b16 v139, v30 offset:49664
	ds_write_b16_d16_hi v140, v30 offset:49792
	ds_write_b16 v141, v31 offset:49920
	ds_write_b16_d16_hi v142, v31 offset:50048
	ds_write_b128 v146, v[4:7] offset:32768
	s_waitcnt vmcnt(10)
	ds_write_b16 v147, v20 offset:49152
	ds_write_b16_d16_hi v148, v20 offset:49280
	ds_write_b16 v149, v21 offset:49408
	ds_write_b16_d16_hi v150, v21 offset:49536
	ds_write_b16 v151, v22 offset:49664
	ds_write_b16_d16_hi v152, v22 offset:49792
	ds_write_b16 v153, v23 offset:49920
	ds_write_b16_d16_hi v154, v23 offset:50048
	ds_write_b128 v156, v[8:11] offset:32768
	s_waitcnt vmcnt(9)
	ds_write_b16 v157, v24 offset:49152
	ds_write_b16_d16_hi v158, v24 offset:49280
	ds_write_b16 v159, v25 offset:49408
	ds_write_b16_d16_hi v160, v25 offset:49536
	ds_write_b16 v161, v26 offset:49664
	ds_write_b16_d16_hi v162, v26 offset:49792
	ds_write_b16 v163, v27 offset:49920
	ds_write_b16_d16_hi v164, v27 offset:50048
	ds_write_b128 v165, v[0:3] offset:32768
	s_waitcnt vmcnt(8)
	ds_write_b16 v166, v12 offset:49152
	ds_write_b16_d16_hi v167, v12 offset:49280
	ds_write_b16 v168, v13 offset:49408
	ds_write_b16_d16_hi v169, v13 offset:49536
	ds_write_b16 v170, v14 offset:49664
	ds_write_b16_d16_hi v171, v14 offset:49792
	ds_write_b16 v172, v15 offset:49920
	ds_write_b16_d16_hi v173, v15 offset:50048
	s_waitcnt lgkmcnt(0)
	s_barrier
	v_mfma_f32_32x32x16_bf16 a[48:63], v[84:87], v[92:95], a[48:63]
	ds_read_b128 v[0:3], v143 offset:0x8000
	ds_read_b128 v[4:7], v143 offset:0x9000
	ds_read_b128 v[8:11], v132 offset:0x8000
	ds_read_b128 v[12:15], v177 offset:0x9000
	ds_read_b128 v[16:19], v39 offset:0x8000
	ds_read_b128 v[20:23], v39 offset:0x9000
	ds_read_b128 v[24:27], v145 offset:0x8000
	v_mfma_f32_32x32x16_bf16 a[48:63], v[100:103], v[108:111], a[48:63]
	ds_read_b128 v[28:31], v180 offset:0x9000
	v_mfma_f32_32x32x16_bf16 a[32:47], v[68:71], v[80:83], 0
	ds_read_b128 v[68:71], v144 offset:0x8000
	v_mfma_f32_32x32x16_bf16 a[16:31], v[72:75], v[76:79], 0
	v_mfma_f32_32x32x16_bf16 a[0:15], v[72:75], v[80:83], 0
	ds_read_b128 v[72:75], v144 offset:0x9000
	ds_read_b128 v[76:79], v133 offset:0x8000
	ds_read_b128 v[80:83], v178 offset:0x9000
	v_mfma_f32_32x32x16_bf16 a[48:63], v[116:119], v[124:127], a[48:63]
	v_mfma_f32_32x32x16_bf16 a[32:47], v[84:87], v[96:99], a[32:47]
	ds_read_b128 v[84:87], v155 offset:0x8000
	v_mfma_f32_32x32x16_bf16 a[16:31], v[88:91], v[92:95], a[16:31]
	v_mfma_f32_32x32x16_bf16 a[0:15], v[88:91], v[96:99], a[0:15]
	ds_read_b128 v[88:91], v155 offset:0x9000
	ds_read_b128 v[92:95], v174 offset:0x8000
	ds_read_b128 v[96:99], v181 offset:0x9000
	s_waitcnt lgkmcnt(12)
	s_waitcnt lgkmcnt(8)
	s_waitcnt lgkmcnt(4)
	s_nop 0
	v_mfma_f32_32x32x16_bf16 a[48:63], v[0:3], v[8:11], a[48:63]
	s_waitcnt lgkmcnt(0)
	s_waitcnt vmcnt(7)
	ds_write_b128 v134, v[40:43]
	s_waitcnt vmcnt(3)
	ds_write_b16 v135, v52 offset:16384
	ds_write_b16_d16_hi v136, v52 offset:16512
	ds_write_b16 v137, v53 offset:16640
	ds_write_b16_d16_hi v138, v53 offset:16768
	ds_write_b16 v139, v54 offset:16896
	ds_write_b16_d16_hi v140, v54 offset:17024
	ds_write_b16 v141, v55 offset:17152
	ds_write_b16_d16_hi v142, v55 offset:17280
	ds_write_b128 v146, v[32:35]
	s_waitcnt vmcnt(2)
	ds_write_b16 v147, v56 offset:16384
	ds_write_b16_d16_hi v148, v56 offset:16512
	ds_write_b16 v149, v57 offset:16640
	ds_write_b16_d16_hi v150, v57 offset:16768
	ds_write_b16 v151, v58 offset:16896
	ds_write_b16_d16_hi v152, v58 offset:17024
	ds_write_b16 v153, v59 offset:17152
	ds_write_b16_d16_hi v154, v59 offset:17280
	ds_write_b128 v156, v[44:47]
	s_waitcnt vmcnt(1)
	ds_write_b16 v157, v60 offset:16384
	ds_write_b16_d16_hi v158, v60 offset:16512
	ds_write_b16 v159, v61 offset:16640
	ds_write_b16_d16_hi v160, v61 offset:16768
	ds_write_b16 v161, v62 offset:16896
	ds_write_b16_d16_hi v162, v62 offset:17024
	ds_write_b16 v163, v63 offset:17152
	ds_write_b16_d16_hi v164, v63 offset:17280
	ds_write_b128 v165, v[48:51]
	s_waitcnt vmcnt(0)
	ds_write_b16 v166, v64 offset:16384
	ds_write_b16_d16_hi v167, v64 offset:16512
	ds_write_b16 v168, v65 offset:16640
	ds_write_b16_d16_hi v169, v65 offset:16768
	ds_write_b16 v170, v66 offset:16896
	ds_write_b16_d16_hi v171, v66 offset:17024
	ds_write_b16 v172, v67 offset:17152
	ds_write_b16_d16_hi v173, v67 offset:17280
	s_waitcnt lgkmcnt(0)
	s_barrier
	v_mfma_f32_32x32x16_bf16 a[48:63], v[16:19], v[24:27], a[48:63]
	v_mfma_f32_32x32x16_bf16 a[32:47], v[100:103], v[112:115], a[32:47]
	v_mfma_f32_32x32x16_bf16 a[48:63], v[68:71], v[76:79], a[48:63]
	v_mfma_f32_32x32x16_bf16 a[16:31], v[104:107], v[108:111], a[16:31]
	v_mfma_f32_32x32x16_bf16 a[0:15], v[104:107], v[112:115], a[0:15]
	v_mfma_f32_32x32x16_bf16 a[32:47], v[116:119], v[128:131], a[32:47]
	v_mfma_f32_32x32x16_bf16 a[48:63], v[84:87], v[92:95], a[48:63]
	v_mfma_f32_32x32x16_bf16 a[16:31], v[120:123], v[124:127], a[16:31]
	v_mfma_f32_32x32x16_bf16 a[0:15], v[120:123], v[128:131], a[0:15]
	v_mfma_f32_32x32x16_bf16 a[32:47], v[0:3], v[12:15], a[32:47]
	v_and_b32_e32 v0, 64, v36
	v_lshrrev_b32_e32 v1, 3, v36
	v_and_or_b32 v2, v1, 4, v0
	v_or_b32_e32 v0, s7, v37
	v_add_u32_e32 v0, v0, v38
	s_nop 3
	v_accvgpr_read_b32 v3, a48
	v_ashrrev_i32_e32 v1, 31, v0
	v_lshlrev_b32_e32 v192, 16, v2
	v_mul_f32_e32 v2, 0x3ab504f3, v3
	v_lshl_add_u64 v[0:1], v[0:1], 1, s[0:1]
	v_bfe_u32 v3, v2, 16, 1
	v_mfma_f32_32x32x16_bf16 a[16:31], v[4:7], v[8:11], a[16:31]
	v_add3_u32 v2, v2, v3, s80
	s_mov_b32 s0, 0x20000
	v_accvgpr_read_b32 v8, a51
	v_accvgpr_read_b32 v10, a52
	v_mul_f32_e32 v10, 0x3ab504f3, v10
	v_mov_b32_e32 v9, v193
	v_accvgpr_read_b32 v11, a53
	v_mfma_f32_32x32x16_bf16 a[0:15], v[4:7], v[12:15], a[0:15]
	v_accvgpr_read_b32 v6, a49
	v_lshl_add_u64 v[4:5], v[0:1], 0, v[192:193]
	global_store_short_d16_hi v[4:5], v2, off
	v_mul_f32_e32 v2, 0x3ab504f3, v6
	v_bfe_u32 v3, v2, 16, 1
	v_accvgpr_read_b32 v7, a50
	v_add3_u32 v2, v2, v3, s80
	global_store_short_d16_hi v[4:5], v2, off offset:512
	v_mul_f32_e32 v2, 0x3ab504f3, v7
	v_bfe_u32 v3, v2, 16, 1
	v_add_co_u32_e32 v6, vcc, s0, v4
	v_add3_u32 v2, v2, v3, s80
	s_nop 0
	v_addc_co_u32_e32 v7, vcc, 0, v5, vcc
	global_store_short_d16_hi v[6:7], v2, off
	v_mul_f32_e32 v2, 0x3ab504f3, v8
	v_bfe_u32 v3, v2, 16, 1
	v_add3_u32 v2, v2, v3, s80
	v_or_b32_e32 v8, 0x80000, v192
	v_bfe_u32 v14, v10, 16, 1
	global_store_short_d16_hi v[6:7], v2, off offset:512
	v_lshl_add_u64 v[2:3], v[0:1], 0, v[8:9]
	v_add3_u32 v10, v10, v14, s80
	global_store_short_d16_hi v[2:3], v10, off
	v_mul_f32_e32 v10, 0x3ab504f3, v11
	v_bfe_u32 v11, v10, 16, 1
	v_accvgpr_read_b32 v12, a54
	v_add3_u32 v10, v10, v11, s80
	global_store_short_d16_hi v[2:3], v10, off offset:512
	v_mul_f32_e32 v10, 0x3ab504f3, v12
	v_bfe_u32 v11, v10, 16, 1
	v_add_co_u32_e32 v2, vcc, s0, v2
	v_accvgpr_read_b32 v13, a55
	v_add3_u32 v10, v10, v11, s80
	v_addc_co_u32_e32 v3, vcc, 0, v3, vcc
	global_store_short_d16_hi v[2:3], v10, off
	v_mul_f32_e32 v10, 0x3ab504f3, v13
	v_mfma_f32_32x32x16_bf16 a[32:47], v[16:19], v[28:31], a[32:47]
	v_bfe_u32 v11, v10, 16, 1
	v_accvgpr_read_b32 v12, a56
	v_add3_u32 v10, v10, v11, s80
	v_mul_f32_e32 v12, 0x3ab504f3, v12
	global_store_short_d16_hi v[2:3], v10, off offset:512
	v_or_b32_e32 v10, 0x100000, v192
	v_mov_b32_e32 v11, v193
	v_bfe_u32 v16, v12, 16, 1
	v_accvgpr_read_b32 v13, a57
	v_lshl_add_u64 v[2:3], v[0:1], 0, v[10:11]
	v_add3_u32 v12, v12, v16, s80
	global_store_short_d16_hi v[2:3], v12, off
	v_mul_f32_e32 v12, 0x3ab504f3, v13
	v_bfe_u32 v13, v12, 16, 1
	v_accvgpr_read_b32 v14, a58
	v_add3_u32 v12, v12, v13, s80
	global_store_short_d16_hi v[2:3], v12, off offset:512
	v_mul_f32_e32 v12, 0x3ab504f3, v14
	v_mfma_f32_32x32x16_bf16 a[32:47], v[68:71], v[80:83], a[32:47]
	v_bfe_u32 v13, v12, 16, 1
	v_add_co_u32_e32 v2, vcc, s0, v2
	v_accvgpr_read_b32 v15, a59
	v_add3_u32 v12, v12, v13, s80
	v_addc_co_u32_e32 v3, vcc, 0, v3, vcc
	global_store_short_d16_hi v[2:3], v12, off
	v_mul_f32_e32 v12, 0x3ab504f3, v15
	v_bfe_u32 v13, v12, 16, 1
	v_accvgpr_read_b32 v14, a60
	v_add3_u32 v12, v12, v13, s80
	v_mul_f32_e32 v14, 0x3ab504f3, v14
	global_store_short_d16_hi v[2:3], v12, off offset:512
	v_or_b32_e32 v12, 0x180000, v192
	v_mov_b32_e32 v13, v193
	v_bfe_u32 v18, v14, 16, 1
	v_accvgpr_read_b32 v15, a61
	v_lshl_add_u64 v[2:3], v[0:1], 0, v[12:13]
	v_add3_u32 v14, v14, v18, s80
	global_store_short_d16_hi v[2:3], v14, off
	v_mul_f32_e32 v14, 0x3ab504f3, v15
	v_mfma_f32_32x32x16_bf16 a[32:47], v[84:87], v[96:99], a[32:47]
	v_bfe_u32 v15, v14, 16, 1
	v_accvgpr_read_b32 v16, a62
	v_add3_u32 v14, v14, v15, s80
	global_store_short_d16_hi v[2:3], v14, off offset:512
	v_mul_f32_e32 v14, 0x3ab504f3, v16
	v_bfe_u32 v15, v14, 16, 1
	v_add_co_u32_e32 v2, vcc, s0, v2
	v_accvgpr_read_b32 v17, a63
	v_add3_u32 v14, v14, v15, s80
	v_addc_co_u32_e32 v3, vcc, 0, v3, vcc
	global_store_short_d16_hi v[2:3], v14, off
	v_mul_f32_e32 v14, 0x3ab504f3, v17
	v_bfe_u32 v15, v14, 16, 1
	v_add3_u32 v14, v14, v15, s80
	global_store_short_d16_hi v[2:3], v14, off offset:512
	v_accvgpr_read_b32 v14, a32
	v_mul_f32_e32 v14, 0x3ab504f3, v14
	v_bfe_u32 v18, v14, 16, 1
	v_accvgpr_read_b32 v15, a33
	v_add3_u32 v14, v14, v18, s80
	global_store_short_d16_hi v[4:5], v14, off offset:64
	v_mul_f32_e32 v14, 0x3ab504f3, v15
	v_bfe_u32 v15, v14, 16, 1
	v_accvgpr_read_b32 v16, a34
	v_add3_u32 v14, v14, v15, s80
	global_store_short_d16_hi v[4:5], v14, off offset:576
	v_mul_f32_e32 v4, 0x3ab504f3, v16
	v_bfe_u32 v5, v4, 16, 1
	v_accvgpr_read_b32 v17, a35
	v_add3_u32 v4, v4, v5, s80
	global_store_short_d16_hi v[6:7], v4, off offset:64
	v_mul_f32_e32 v4, 0x3ab504f3, v17
	v_bfe_u32 v5, v4, 16, 1
	v_add3_u32 v4, v4, v5, s80
	global_store_short_d16_hi v[6:7], v4, off offset:576
	v_accvgpr_read_b32 v6, a36
	v_lshl_add_u64 v[2:3], v[0:1], 0, 64
	v_mul_f32_e32 v6, 0x3ab504f3, v6
	v_lshl_add_u64 v[4:5], v[2:3], 0, v[8:9]
	v_bfe_u32 v8, v6, 16, 1
	v_accvgpr_read_b32 v7, a37
	v_add3_u32 v6, v6, v8, s80
	global_store_short_d16_hi v[4:5], v6, off
	v_mul_f32_e32 v6, 0x3ab504f3, v7
	v_bfe_u32 v7, v6, 16, 1
	v_accvgpr_read_b32 v14, a38
	v_add3_u32 v6, v6, v7, s80
	global_store_short_d16_hi v[4:5], v6, off offset:512
	v_mul_f32_e32 v6, 0x3ab504f3, v14
	v_bfe_u32 v7, v6, 16, 1
	v_add_co_u32_e32 v4, vcc, s0, v4
	v_accvgpr_read_b32 v15, a39
	v_add3_u32 v6, v6, v7, s80
	v_addc_co_u32_e32 v5, vcc, 0, v5, vcc
	global_store_short_d16_hi v[4:5], v6, off
	v_mul_f32_e32 v6, 0x3ab504f3, v15
	v_bfe_u32 v7, v6, 16, 1
	v_add3_u32 v6, v6, v7, s80
	v_mfma_f32_32x32x16_bf16 a[16:31], v[20:23], v[24:27], a[16:31]
	global_store_short_d16_hi v[4:5], v6, off offset:512
	v_accvgpr_read_b32 v6, a40
	v_mul_f32_e32 v6, 0x3ab504f3, v6
	v_lshl_add_u64 v[4:5], v[2:3], 0, v[10:11]
	v_bfe_u32 v10, v6, 16, 1
	v_accvgpr_read_b32 v7, a41
	v_add3_u32 v6, v6, v10, s80
	global_store_short_d16_hi v[4:5], v6, off
	v_mul_f32_e32 v6, 0x3ab504f3, v7
	v_bfe_u32 v7, v6, 16, 1
	v_accvgpr_read_b32 v8, a42
	v_add3_u32 v6, v6, v7, s80
	global_store_short_d16_hi v[4:5], v6, off offset:512
	v_mul_f32_e32 v6, 0x3ab504f3, v8
	v_mfma_f32_32x32x16_bf16 a[16:31], v[72:75], v[76:79], a[16:31]
	v_bfe_u32 v7, v6, 16, 1
	v_add_co_u32_e32 v4, vcc, s0, v4
	v_accvgpr_read_b32 v9, a43
	v_add3_u32 v6, v6, v7, s80
	v_addc_co_u32_e32 v5, vcc, 0, v5, vcc
	global_store_short_d16_hi v[4:5], v6, off
	v_mul_f32_e32 v6, 0x3ab504f3, v9
	v_bfe_u32 v7, v6, 16, 1
	v_add3_u32 v6, v6, v7, s80
	global_store_short_d16_hi v[4:5], v6, off offset:512
	v_accvgpr_read_b32 v6, a44
	v_mul_f32_e32 v6, 0x3ab504f3, v6
	v_bfe_u32 v10, v6, 16, 1
	v_mfma_f32_32x32x16_bf16 a[16:31], v[88:91], v[92:95], a[16:31]
	v_accvgpr_read_b32 v7, a45
	v_lshl_add_u64 v[4:5], v[2:3], 0, v[12:13]
	v_add3_u32 v6, v6, v10, s80
	global_store_short_d16_hi v[4:5], v6, off
	v_mul_f32_e32 v6, 0x3ab504f3, v7
	v_bfe_u32 v7, v6, 16, 1
	v_accvgpr_read_b32 v8, a46
	v_add3_u32 v6, v6, v7, s80
	global_store_short_d16_hi v[4:5], v6, off offset:512
	v_mul_f32_e32 v6, 0x3ab504f3, v8
	v_bfe_u32 v7, v6, 16, 1
	v_add_co_u32_e32 v4, vcc, s0, v4
	v_accvgpr_read_b32 v9, a47
	v_add3_u32 v6, v6, v7, s80
	v_addc_co_u32_e32 v5, vcc, 0, v5, vcc
	global_store_short_d16_hi v[4:5], v6, off
	v_mul_f32_e32 v6, 0x3ab504f3, v9
	v_bfe_u32 v7, v6, 16, 1
	v_accvgpr_read_b32 v8, a16
	v_add3_u32 v6, v6, v7, s80
	v_mul_f32_e32 v8, 0x3ab504f3, v8
	global_store_short_d16_hi v[4:5], v6, off offset:512
	v_or_b32_e32 v4, 0x200000, v192
	v_mov_b32_e32 v5, v193
	v_bfe_u32 v12, v8, 16, 1
	v_accvgpr_read_b32 v9, a17
	v_lshl_add_u64 v[6:7], v[0:1], 0, v[4:5]
	v_add3_u32 v8, v8, v12, s80
	global_store_short_d16_hi v[6:7], v8, off
	v_mul_f32_e32 v8, 0x3ab504f3, v9
	v_bfe_u32 v9, v8, 16, 1
	v_accvgpr_read_b32 v10, a18
	v_add3_u32 v8, v8, v9, s80
	global_store_short_d16_hi v[6:7], v8, off offset:512
	v_mul_f32_e32 v8, 0x3ab504f3, v10
	v_bfe_u32 v9, v8, 16, 1
	v_add_co_u32_e32 v6, vcc, s0, v6
	v_accvgpr_read_b32 v11, a19
	v_add3_u32 v8, v8, v9, s80
	v_addc_co_u32_e32 v7, vcc, 0, v7, vcc
	global_store_short_d16_hi v[6:7], v8, off
	v_mul_f32_e32 v8, 0x3ab504f3, v11
	v_bfe_u32 v9, v8, 16, 1
	v_accvgpr_read_b32 v10, a20
	v_add3_u32 v8, v8, v9, s80
	v_mul_f32_e32 v10, 0x3ab504f3, v10
	global_store_short_d16_hi v[6:7], v8, off offset:512
	v_or_b32_e32 v6, 0x280000, v192
	v_mov_b32_e32 v7, v193
	v_bfe_u32 v14, v10, 16, 1
	v_accvgpr_read_b32 v11, a21
	v_lshl_add_u64 v[8:9], v[0:1], 0, v[6:7]
	v_add3_u32 v10, v10, v14, s80
	global_store_short_d16_hi v[8:9], v10, off
	v_mul_f32_e32 v10, 0x3ab504f3, v11
	v_bfe_u32 v11, v10, 16, 1
	v_accvgpr_read_b32 v12, a22
	v_add3_u32 v10, v10, v11, s80
	global_store_short_d16_hi v[8:9], v10, off offset:512
	v_mul_f32_e32 v10, 0x3ab504f3, v12
	v_bfe_u32 v11, v10, 16, 1
	v_add_co_u32_e32 v8, vcc, s0, v8
	v_accvgpr_read_b32 v13, a23
	v_add3_u32 v10, v10, v11, s80
	v_addc_co_u32_e32 v9, vcc, 0, v9, vcc
	global_store_short_d16_hi v[8:9], v10, off
	v_mul_f32_e32 v10, 0x3ab504f3, v13
	v_bfe_u32 v11, v10, 16, 1
	v_accvgpr_read_b32 v12, a24
	v_add3_u32 v10, v10, v11, s80
	v_mul_f32_e32 v12, 0x3ab504f3, v12
	v_mfma_f32_32x32x16_bf16 a[0:15], v[20:23], v[28:31], a[0:15]
	global_store_short_d16_hi v[8:9], v10, off offset:512
	v_or_b32_e32 v8, 0x300000, v192
	v_mov_b32_e32 v9, v193
	v_bfe_u32 v16, v12, 16, 1
	v_accvgpr_read_b32 v13, a25
	v_lshl_add_u64 v[10:11], v[0:1], 0, v[8:9]
	v_add3_u32 v12, v12, v16, s80
	global_store_short_d16_hi v[10:11], v12, off
	v_mul_f32_e32 v12, 0x3ab504f3, v13
	v_bfe_u32 v13, v12, 16, 1
	v_accvgpr_read_b32 v14, a26
	v_add3_u32 v12, v12, v13, s80
	global_store_short_d16_hi v[10:11], v12, off offset:512
	v_mul_f32_e32 v12, 0x3ab504f3, v14
	v_bfe_u32 v13, v12, 16, 1
	v_add_co_u32_e32 v10, vcc, s0, v10
	v_accvgpr_read_b32 v15, a27
	v_add3_u32 v12, v12, v13, s80
	v_addc_co_u32_e32 v11, vcc, 0, v11, vcc
	v_mfma_f32_32x32x16_bf16 a[0:15], v[72:75], v[80:83], a[0:15]
	global_store_short_d16_hi v[10:11], v12, off
	v_mul_f32_e32 v12, 0x3ab504f3, v15
	v_bfe_u32 v13, v12, 16, 1
	v_add3_u32 v12, v12, v13, s80
	global_store_short_d16_hi v[10:11], v12, off offset:512
	v_accvgpr_read_b32 v10, a28
	v_mul_f32_e32 v10, 0x3ab504f3, v10
	v_or_b32_e32 v192, 0x380000, v192
	v_bfe_u32 v14, v10, 16, 1
	v_accvgpr_read_b32 v11, a29
	v_lshl_add_u64 v[0:1], v[0:1], 0, v[192:193]
	v_add3_u32 v10, v10, v14, s80
	global_store_short_d16_hi v[0:1], v10, off
	v_mul_f32_e32 v10, 0x3ab504f3, v11
	v_mfma_f32_32x32x16_bf16 a[0:15], v[88:91], v[96:99], a[0:15]
	v_bfe_u32 v11, v10, 16, 1
	v_accvgpr_read_b32 v12, a30
	v_add3_u32 v10, v10, v11, s80
	global_store_short_d16_hi v[0:1], v10, off offset:512
	v_mul_f32_e32 v10, 0x3ab504f3, v12
	v_bfe_u32 v11, v10, 16, 1
	v_add_co_u32_e32 v0, vcc, s0, v0
	v_accvgpr_read_b32 v13, a31
	v_add3_u32 v10, v10, v11, s80
	v_addc_co_u32_e32 v1, vcc, 0, v1, vcc
	global_store_short_d16_hi v[0:1], v10, off
	v_mul_f32_e32 v10, 0x3ab504f3, v13
	v_bfe_u32 v11, v10, 16, 1
	v_add3_u32 v10, v10, v11, s80
	global_store_short_d16_hi v[0:1], v10, off offset:512
	v_accvgpr_read_b32 v10, a0
	v_lshl_add_u64 v[0:1], v[2:3], 0, v[4:5]
	v_mul_f32_e32 v4, 0x3ab504f3, v10
	v_bfe_u32 v5, v4, 16, 1
	v_accvgpr_read_b32 v11, a1
	v_add3_u32 v4, v4, v5, s80
	global_store_short_d16_hi v[0:1], v4, off
	v_mul_f32_e32 v4, 0x3ab504f3, v11
	v_bfe_u32 v5, v4, 16, 1
	v_accvgpr_read_b32 v12, a2
	v_add3_u32 v4, v4, v5, s80
	global_store_short_d16_hi v[0:1], v4, off offset:512
	v_mul_f32_e32 v4, 0x3ab504f3, v12
	v_bfe_u32 v5, v4, 16, 1
	v_add_co_u32_e32 v0, vcc, s0, v0
	v_accvgpr_read_b32 v13, a3
	v_add3_u32 v4, v4, v5, s80
	v_addc_co_u32_e32 v1, vcc, 0, v1, vcc
	global_store_short_d16_hi v[0:1], v4, off
	v_mul_f32_e32 v4, 0x3ab504f3, v13
	v_bfe_u32 v5, v4, 16, 1
	v_add3_u32 v4, v4, v5, s80
	global_store_short_d16_hi v[0:1], v4, off offset:512
	v_accvgpr_read_b32 v4, a4
	v_mul_f32_e32 v4, 0x3ab504f3, v4
	v_lshl_add_u64 v[0:1], v[2:3], 0, v[6:7]
	v_bfe_u32 v6, v4, 16, 1
	v_accvgpr_read_b32 v5, a5
	v_add3_u32 v4, v4, v6, s80
	global_store_short_d16_hi v[0:1], v4, off
	v_mul_f32_e32 v4, 0x3ab504f3, v5
	v_bfe_u32 v5, v4, 16, 1
	v_accvgpr_read_b32 v10, a6
	v_add3_u32 v4, v4, v5, s80
	global_store_short_d16_hi v[0:1], v4, off offset:512
	v_mul_f32_e32 v4, 0x3ab504f3, v10
	v_bfe_u32 v5, v4, 16, 1
	v_add_co_u32_e32 v0, vcc, s0, v0
	v_accvgpr_read_b32 v11, a7
	v_add3_u32 v4, v4, v5, s80
	v_addc_co_u32_e32 v1, vcc, 0, v1, vcc
	global_store_short_d16_hi v[0:1], v4, off
	v_mul_f32_e32 v4, 0x3ab504f3, v11
	v_bfe_u32 v5, v4, 16, 1
	v_add3_u32 v4, v4, v5, s80
	global_store_short_d16_hi v[0:1], v4, off offset:512
	v_accvgpr_read_b32 v4, a8
	v_mul_f32_e32 v4, 0x3ab504f3, v4
	v_lshl_add_u64 v[0:1], v[2:3], 0, v[8:9]
	v_bfe_u32 v8, v4, 16, 1
	v_accvgpr_read_b32 v5, a9
	v_add3_u32 v4, v4, v8, s80
	global_store_short_d16_hi v[0:1], v4, off
	v_mul_f32_e32 v4, 0x3ab504f3, v5
	v_bfe_u32 v5, v4, 16, 1
	v_accvgpr_read_b32 v6, a10
	v_add3_u32 v4, v4, v5, s80
	global_store_short_d16_hi v[0:1], v4, off offset:512
	v_mul_f32_e32 v4, 0x3ab504f3, v6
	v_bfe_u32 v5, v4, 16, 1
	v_add_co_u32_e32 v0, vcc, s0, v0
	v_accvgpr_read_b32 v7, a11
	v_add3_u32 v4, v4, v5, s80
	v_addc_co_u32_e32 v1, vcc, 0, v1, vcc
	global_store_short_d16_hi v[0:1], v4, off
	v_mul_f32_e32 v4, 0x3ab504f3, v7
	v_bfe_u32 v5, v4, 16, 1
	v_add3_u32 v4, v4, v5, s80
	global_store_short_d16_hi v[0:1], v4, off offset:512
	v_accvgpr_read_b32 v4, a12
	v_lshl_add_u64 v[0:1], v[2:3], 0, v[192:193]
	v_mul_f32_e32 v2, 0x3ab504f3, v4
	v_bfe_u32 v3, v2, 16, 1
	v_accvgpr_read_b32 v5, a13
	v_add3_u32 v2, v2, v3, s80
	global_store_short_d16_hi v[0:1], v2, off
	v_mul_f32_e32 v2, 0x3ab504f3, v5
	v_bfe_u32 v3, v2, 16, 1
	v_accvgpr_read_b32 v6, a14
	v_add3_u32 v2, v2, v3, s80
	global_store_short_d16_hi v[0:1], v2, off offset:512
	v_mul_f32_e32 v2, 0x3ab504f3, v6
	v_bfe_u32 v3, v2, 16, 1
	v_add_co_u32_e32 v0, vcc, 0x20000, v0
	v_accvgpr_read_b32 v7, a15
	v_add3_u32 v2, v2, v3, s80
	v_addc_co_u32_e32 v1, vcc, 0, v1, vcc
	global_store_short_d16_hi v[0:1], v2, off
	v_mul_f32_e32 v2, 0x3ab504f3, v7
	v_bfe_u32 v3, v2, 16, 1
	v_add3_u32 v2, v2, v3, s80
	global_store_short_d16_hi v[0:1], v2, off offset:512
	s_cbranch_execnz .LBB0_249

.LBB0_374:
	s_andn2_b64 vcc, exec, s[0:1]
	s_cbranch_vccnz .LBB0_376
	s_add_i32 s5, s97, 0xfffffbe0
	s_lshr_b32 s78, s5, 8
	s_lshl_b64 s[0:1], s[78:79], 23
	v_readlane_b32 s2, v254, 5
	s_add_u32 s0, s2, s0
	v_readlane_b32 s2, v254, 6
	s_addc_u32 s1, s2, s1
	s_lshl_b64 s[2:3], s[78:79], 22
	v_readlane_b32 s4, v254, 11
	s_waitcnt vmcnt(7)
	v_mov_b32_e32 v37, v208
	s_add_u32 s2, s4, s2
	v_readlane_b32 s4, v254, 12
	s_addc_u32 s3, s4, s3
	v_lshlrev_b32_e32 v1, 7, v37
	s_lshl_b32 s4, s97, 7
	v_lshrrev_b32_e32 v0, 5, v37
	v_and_b32_e32 v5, 7, v37
	v_and_b32_e32 v39, 0x2f80, v1
	v_ashrrev_i32_e32 v1, 1, v37
	s_and_b32 s4, s4, 0x80
	v_and_b32_e32 v36, 31, v37
	v_and_b32_e32 v38, 0xffffffc0, v1
	v_bitop3_b32 v0, v0, v5, 1 bitop3:0x6c
	v_ashrrev_i32_e32 v110, 3, v37
	v_or_b32_e32 v1, v38, v36
	v_lshlrev_b32_e32 v109, 4, v0
	v_add_u32_e32 v0, s4, v110
	v_lshl_add_u32 v108, v1, 7, v214
	v_ashrrev_i32_e32 v1, 31, v0
	v_readlane_b32 s6, v253, 40
	v_lshlrev_b64 v[0:1], 8, v[0:1]
	v_readlane_b32 s7, v253, 41
	v_lshlrev_b32_e32 v3, 4, v37
	v_and_b32_e32 v192, 0x70, v3
	v_lshl_add_u64 v[0:1], s[6:7], 0, v[0:1]
	v_lshl_add_u64 v[32:33], v[0:1], 0, v[192:193]
	global_load_dwordx4 v[40:43], v[32:33], off
	v_ashrrev_i32_e32 v86, 4, v37
	s_lshl_b32 s5, s5, 6
	v_ashrrev_i32_e32 v87, 31, v86
	s_and_b32 s5, s5, 0x3f80
	v_lshlrev_b32_e32 v2, 3, v37
	v_lshlrev_b64 v[0:1], 15, v[86:87]
	v_lshl_add_u64 v[0:1], s[2:3], 0, v[0:1]
	s_lshl_b32 s78, s5, 1
	v_and_b32_e32 v87, 0x78, v2
	v_add_u32_e32 v7, 0x100, v37
	v_lshl_add_u64 v[0:1], v[0:1], 0, s[78:79]
	v_lshlrev_b32_e32 v2, 1, v87
	v_mov_b32_e32 v3, v193
	v_ashrrev_i32_e32 v111, 3, v7
	v_lshl_add_u64 v[12:13], v[0:1], 0, v[2:3]
	v_add_u32_e32 v0, s4, v111
	v_ashrrev_i32_e32 v1, 31, v0
	v_lshlrev_b64 v[0:1], 8, v[0:1]
	v_bfe_u32 v4, v37, 5, 1
	v_lshl_add_u64 v[0:1], s[6:7], 0, v[0:1]
	v_lshl_add_u64 v[34:35], v[0:1], 0, v[192:193]
	v_bitop3_b32 v0, v4, v5, 4 bitop3:0x36
	v_ashrrev_i32_e32 v88, 4, v7
	v_lshlrev_b32_e32 v113, 4, v0
	v_bitop3_b32 v0, v4, v5, 6 bitop3:0x36
	v_ashrrev_i32_e32 v89, 31, v88
	v_lshlrev_b32_e32 v114, 4, v0
	v_lshlrev_b64 v[0:1], 15, v[88:89]
	v_bitop3_b32 v6, v4, v5, 2 bitop3:0x36
	v_lshl_add_u64 v[0:1], s[2:3], 0, v[0:1]
	v_add_u32_e32 v4, 0x200, v37
	v_lshl_add_u64 v[0:1], v[0:1], 0, s[78:79]
	v_ashrrev_i32_e32 v89, 3, v4
	v_lshl_add_u64 v[14:15], v[0:1], 0, v[2:3]
	v_add_u32_e32 v0, s4, v89
	v_ashrrev_i32_e32 v1, 31, v0
	v_lshlrev_b64 v[0:1], 8, v[0:1]
	v_ashrrev_i32_e32 v94, 4, v4
	v_lshl_add_u64 v[0:1], s[6:7], 0, v[0:1]
	v_ashrrev_i32_e32 v95, 31, v94
	v_lshl_add_u64 v[90:91], v[0:1], 0, v[192:193]
	v_lshlrev_b64 v[0:1], 15, v[94:95]
	v_lshl_add_u64 v[0:1], s[2:3], 0, v[0:1]
	v_add_u32_e32 v8, 0x300, v37
	v_lshl_add_u64 v[0:1], v[0:1], 0, s[78:79]
	v_ashrrev_i32_e32 v95, 3, v8
	v_lshl_add_u64 v[24:25], v[0:1], 0, v[2:3]
	v_add_u32_e32 v0, s4, v95
	v_ashrrev_i32_e32 v1, 31, v0
	v_lshlrev_b64 v[0:1], 8, v[0:1]
	v_ashrrev_i32_e32 v98, 4, v8
	v_lshl_add_u64 v[0:1], s[6:7], 0, v[0:1]
	v_ashrrev_i32_e32 v99, 31, v98
	v_lshl_add_u64 v[96:97], v[0:1], 0, v[192:193]
	v_lshlrev_b64 v[0:1], 15, v[98:99]
	v_lshl_add_u64 v[0:1], s[2:3], 0, v[0:1]
	v_lshl_add_u64 v[0:1], v[0:1], 0, s[78:79]
	v_lshl_add_u64 v[26:27], v[0:1], 0, v[2:3]
	v_xor_b32_e32 v0, v110, v37
	v_lshlrev_b32_e32 v0, 4, v0
	v_and_b32_e32 v0, 0x70, v0
	global_load_dwordx4 v[44:47], v[34:35], off
	global_load_dwordx4 v[48:51], v[12:13], off
	v_lshlrev_b32_e32 v112, 4, v6
	global_load_dwordx4 v[4:7], v[34:35], off offset:128
	global_load_dwordx4 v[52:55], v[14:15], off
	global_load_dwordx4 v[16:19], v[32:33], off offset:128
	global_load_dwordx4 v[56:59], v[90:91], off
	global_load_dwordx4 v[8:11], v[90:91], off offset:128
	s_waitcnt vmcnt(12)
	v_lshl_or_b32 v152, v110, 7, v0
	global_load_dwordx4 v[60:63], v[96:97], off
	global_load_dwordx4 v[64:67], v[24:25], off
	global_load_dwordx4 v[0:3], v[96:97], off offset:128
	global_load_dwordx4 v[82:85], v[26:27], off
	s_mov_b32 s2, 0x200000
	v_add_co_u32_e32 v100, vcc, s2, v12
	s_movk_i32 s3, 0x50
	s_nop 0
	v_addc_co_u32_e32 v101, vcc, 0, v13, vcc
	v_add_co_u32_e32 v102, vcc, s2, v14
	s_movk_i32 s6, 0x60
	s_nop 0
	v_addc_co_u32_e32 v103, vcc, 0, v15, vcc
	v_add_co_u32_e32 v104, vcc, s2, v24
	global_load_dwordx4 v[28:31], v[100:101], off
	global_load_dwordx4 v[20:23], v[102:103], off
	v_addc_co_u32_e32 v105, vcc, 0, v25, vcc
	v_add_co_u32_e32 v106, vcc, s2, v26
	s_movk_i32 s2, 0x70
	s_nop 0
	v_addc_co_u32_e32 v107, vcc, 0, v27, vcc
	global_load_dwordx4 v[24:27], v[104:105], off
	global_load_dwordx4 v[12:15], v[106:107], off
	s_waitcnt vmcnt(15)
	ds_write_b128 v152, v[40:43]
	v_lshlrev_b32_e32 v40, 1, v86
	v_lshlrev_b32_e32 v41, 7, v87
	v_and_b32_e32 v42, -16, v110
	v_and_b32_e32 v40, 14, v40
	v_add_u32_e32 v43, v41, v42
	v_or_b32_e32 v153, v43, v40
	v_xad_u32 v43, v42, 16, v41
	v_or_b32_e32 v154, v43, v40
	v_xad_u32 v43, v42, 32, v41
	v_or_b32_e32 v155, v43, v40
	v_xad_u32 v43, v42, 48, v41
	v_or_b32_e32 v156, v43, v40
	v_xad_u32 v43, v42, 64, v41
	v_or_b32_e32 v157, v43, v40
	v_xad_u32 v43, v42, s3, v41
	v_or_b32_e32 v158, v43, v40
	v_xad_u32 v43, v42, s6, v41
	v_xad_u32 v42, v42, s2, v41
	v_or_b32_e32 v159, v43, v40
	v_or_b32_e32 v160, v42, v40
	v_xor_b32_e32 v40, v111, v37
	v_lshlrev_b32_e32 v40, 4, v40
	v_and_b32_e32 v40, 0x70, v40
	v_lshl_or_b32 v164, v111, 7, v40
	v_lshlrev_b32_e32 v40, 1, v88
	v_and_b32_e32 v42, -16, v111
	v_and_b32_e32 v40, 14, v40
	v_add_u32_e32 v43, v41, v42
	v_or_b32_e32 v165, v43, v40
	v_xad_u32 v43, v42, 16, v41
	v_or_b32_e32 v166, v43, v40
	v_xad_u32 v43, v42, 32, v41
	v_or_b32_e32 v167, v43, v40
	v_xad_u32 v43, v42, 48, v41
	v_or_b32_e32 v168, v43, v40
	v_xad_u32 v43, v42, 64, v41
	v_or_b32_e32 v169, v43, v40
	v_xad_u32 v43, v42, s3, v41
	v_or_b32_e32 v170, v43, v40
	v_xad_u32 v43, v42, s6, v41
	v_xad_u32 v42, v42, s2, v41
	v_or_b32_e32 v171, v43, v40
	v_or_b32_e32 v172, v42, v40
	v_xor_b32_e32 v40, v89, v37
	v_lshlrev_b32_e32 v40, 4, v40
	v_and_b32_e32 v40, 0x70, v40
	v_lshl_or_b32 v174, v89, 7, v40
	v_lshlrev_b32_e32 v40, 1, v94
	v_and_b32_e32 v42, -16, v89
	v_and_b32_e32 v40, 14, v40
	v_add_u32_e32 v43, v41, v42
	v_or_b32_e32 v175, v43, v40
	v_xad_u32 v43, v42, 16, v41
	v_or_b32_e32 v176, v43, v40
	v_xad_u32 v43, v42, 32, v41
	v_or_b32_e32 v177, v43, v40
	v_xad_u32 v43, v42, 48, v41
	v_or_b32_e32 v178, v43, v40
	v_xad_u32 v43, v42, 64, v41
	v_or_b32_e32 v179, v43, v40
	v_xad_u32 v43, v42, s3, v41
	v_or_b32_e32 v180, v43, v40
	v_xad_u32 v43, v42, s6, v41
	v_xad_u32 v42, v42, s2, v41
	v_or_b32_e32 v181, v43, v40
	v_or_b32_e32 v182, v42, v40
	v_xor_b32_e32 v40, v95, v37
	v_lshlrev_b32_e32 v40, 4, v40
	v_and_b32_e32 v40, 0x70, v40
	v_lshl_or_b32 v183, v95, 7, v40
	v_lshlrev_b32_e32 v40, 1, v98
	v_and_b32_e32 v42, -16, v95
	v_and_b32_e32 v40, 14, v40
	v_add_u32_e32 v43, v41, v42
	v_or_b32_e32 v184, v43, v40
	v_xad_u32 v43, v42, 16, v41
	v_or_b32_e32 v185, v43, v40
	v_xad_u32 v43, v42, 32, v41
	v_or_b32_e32 v186, v43, v40
	v_xad_u32 v43, v42, 48, v41
	v_or_b32_e32 v187, v43, v40
	v_xad_u32 v43, v42, 64, v41
	v_or_b32_e32 v188, v43, v40
	v_xad_u32 v43, v42, s3, v41
	v_or_b32_e32 v189, v43, v40
	v_xad_u32 v43, v42, s6, v41
	v_xad_u32 v41, v42, s2, v41
	v_or_b32_e32 v190, v43, v40
	v_or_b32_e32 v191, v41, v40
	v_and_b32_e32 v75, 7, v208
	v_lshlrev_b32_e32 v75, 4, v75
	v_bfe_u32 v92, v208, 3, 2
	v_lshlrev_b32_e32 v92, 4, v92
	v_xor_b32_e32 v153, v75, v153
	v_xor_b32_e32 v154, v75, v154
	v_xor_b32_e32 v155, v75, v155
	v_xor_b32_e32 v156, v75, v156
	v_xor_b32_e32 v157, v75, v157
	v_xor_b32_e32 v158, v75, v158
	v_xor_b32_e32 v159, v75, v159
	v_xor_b32_e32 v160, v75, v160
	v_xor_b32_e32 v165, v75, v165
	v_xor_b32_e32 v166, v75, v166
	v_xor_b32_e32 v167, v75, v167
	v_xor_b32_e32 v168, v75, v168
	v_xor_b32_e32 v169, v75, v169
	v_xor_b32_e32 v170, v75, v170
	v_xor_b32_e32 v171, v75, v171
	v_xor_b32_e32 v172, v75, v172
	v_xor_b32_e32 v175, v75, v175
	v_xor_b32_e32 v176, v75, v176
	v_xor_b32_e32 v177, v75, v177
	v_xor_b32_e32 v178, v75, v178
	v_xor_b32_e32 v179, v75, v179
	v_xor_b32_e32 v180, v75, v180
	v_xor_b32_e32 v181, v75, v181
	v_xor_b32_e32 v182, v75, v182
	v_xor_b32_e32 v184, v75, v184
	v_xor_b32_e32 v185, v75, v185
	v_xor_b32_e32 v186, v75, v186
	v_xor_b32_e32 v187, v75, v187
	v_xor_b32_e32 v188, v75, v188
	v_xor_b32_e32 v189, v75, v189
	v_xor_b32_e32 v190, v75, v190
	v_xor_b32_e32 v191, v75, v191
	s_waitcnt vmcnt(13)
	ds_write_b16 v153, v48 offset:16384
	ds_write_b16_d16_hi v154, v48 offset:16512
	ds_write_b16 v155, v49 offset:16640
	ds_write_b16_d16_hi v156, v49 offset:16768
	ds_write_b16 v157, v50 offset:16896
	ds_write_b16_d16_hi v158, v50 offset:17024
	ds_write_b16 v159, v51 offset:17152
	ds_write_b16_d16_hi v160, v51 offset:17280
	ds_write_b128 v164, v[44:47]
	s_waitcnt vmcnt(11)
	ds_write_b16 v165, v52 offset:16384
	ds_write_b16_d16_hi v166, v52 offset:16512
	ds_write_b16 v167, v53 offset:16640
	ds_write_b16_d16_hi v168, v53 offset:16768
	ds_write_b16 v169, v54 offset:16896
	ds_write_b16_d16_hi v170, v54 offset:17024
	ds_write_b16 v171, v55 offset:17152
	ds_write_b16_d16_hi v172, v55 offset:17280
	s_waitcnt vmcnt(9)
	ds_write_b128 v174, v[56:59]
	s_waitcnt vmcnt(6)
	ds_write_b16 v175, v64 offset:16384
	ds_write_b16_d16_hi v176, v64 offset:16512
	ds_write_b16 v177, v65 offset:16640
	ds_write_b16_d16_hi v178, v65 offset:16768
	ds_write_b16 v179, v66 offset:16896
	ds_write_b16_d16_hi v180, v66 offset:17024
	ds_write_b16 v181, v67 offset:17152
	ds_write_b16_d16_hi v182, v67 offset:17280
	ds_write_b128 v183, v[60:63]
	s_waitcnt vmcnt(4)
	ds_write_b16 v184, v82 offset:16384
	ds_write_b16_d16_hi v185, v82 offset:16512
	ds_write_b16 v186, v83 offset:16640
	ds_write_b16_d16_hi v187, v83 offset:16768
	ds_write_b16 v188, v84 offset:16896
	ds_write_b16_d16_hi v189, v84 offset:17024
	ds_write_b16 v190, v85 offset:17152
	ds_write_b16_d16_hi v191, v85 offset:17280
	s_waitcnt lgkmcnt(0)
	s_barrier
	global_load_dwordx4 v[40:43], v[32:33], off offset:128
	s_nop 0
	global_load_dwordx4 v[32:35], v[34:35], off offset:128
	s_nop 0
	global_load_dwordx4 v[44:47], v[90:91], off offset:128
	global_load_dwordx4 v[48:51], v[96:97], off offset:128
	global_load_dwordx4 v[52:55], v[100:101], off
	global_load_dwordx4 v[56:59], v[102:103], off
	global_load_dwordx4 v[60:63], v[104:105], off
	global_load_dwordx4 v[64:67], v[106:107], off
	v_or_b32_e32 v150, v108, v109
	v_xor_b32_e32 v150, v92, v150
	v_xor_b32_e32 v207, 64, v150
	v_or_b32_e32 v161, v109, v39
	ds_read_b128 v[82:85], v161 offset:0
	ds_read_b128 v[86:89], v161 offset:0x1000
	ds_read_b128 v[94:97], v150 offset:0
	ds_read_b128 v[98:101], v207 offset:0x1000
	v_or_b32_e32 v151, v108, v113
	v_xor_b32_e32 v151, v92, v151
	v_xor_b32_e32 v221, 64, v151
	v_or_b32_e32 v162, v113, v39
	v_or_b32_e32 v163, v108, v112
	v_xor_b32_e32 v163, v92, v163
	v_xor_b32_e32 v224, 64, v163
	v_or_b32_e32 v173, v114, v39
	v_or_b32_e32 v39, v112, v39
	v_or_b32_e32 v192, v108, v114
	v_xor_b32_e32 v192, v92, v192
	v_xor_b32_e32 v225, 64, v192
	ds_read_b128 v[102:105], v39 offset:0
	ds_read_b128 v[106:109], v39 offset:0x1000
	ds_read_b128 v[110:113], v163 offset:0
	ds_read_b128 v[114:117], v224 offset:0x1000
	ds_read_b128 v[118:121], v162 offset:0
	ds_read_b128 v[122:125], v162 offset:0x1000
	ds_read_b128 v[126:129], v151 offset:0
	ds_read_b128 v[130:133], v221 offset:0x1000
	ds_read_b128 v[134:137], v173 offset:0
	ds_read_b128 v[138:141], v173 offset:0x1000
	ds_read_b128 v[142:145], v192 offset:0
	ds_read_b128 v[146:149], v225 offset:0x1000
	s_waitcnt lgkmcnt(12)
	s_nop 0
	v_mfma_f32_32x32x16_bf16 a[48:63], v[82:85], v[94:97], 0
	s_waitcnt lgkmcnt(8)
	s_waitcnt lgkmcnt(4)
	s_waitcnt lgkmcnt(0)
	ds_write_b128 v152, v[16:19] offset:32768
	s_waitcnt vmcnt(11)
	ds_write_b16 v153, v28 offset:49152
	ds_write_b16_d16_hi v154, v28 offset:49280
	ds_write_b16 v155, v29 offset:49408
	ds_write_b16_d16_hi v156, v29 offset:49536
	ds_write_b16 v157, v30 offset:49664
	ds_write_b16_d16_hi v158, v30 offset:49792
	ds_write_b16 v159, v31 offset:49920
	ds_write_b16_d16_hi v160, v31 offset:50048
	ds_write_b128 v164, v[4:7] offset:32768
	s_waitcnt vmcnt(10)
	ds_write_b16 v165, v20 offset:49152
	ds_write_b16_d16_hi v166, v20 offset:49280
	ds_write_b16 v167, v21 offset:49408
	ds_write_b16_d16_hi v168, v21 offset:49536
	ds_write_b16 v169, v22 offset:49664
	ds_write_b16_d16_hi v170, v22 offset:49792
	ds_write_b16 v171, v23 offset:49920
	ds_write_b16_d16_hi v172, v23 offset:50048
	ds_write_b128 v174, v[8:11] offset:32768
	s_waitcnt vmcnt(9)
	ds_write_b16 v175, v24 offset:49152
	ds_write_b16_d16_hi v176, v24 offset:49280
	ds_write_b16 v177, v25 offset:49408
	ds_write_b16_d16_hi v178, v25 offset:49536
	ds_write_b16 v179, v26 offset:49664
	ds_write_b16_d16_hi v180, v26 offset:49792
	ds_write_b16 v181, v27 offset:49920
	ds_write_b16_d16_hi v182, v27 offset:50048
	ds_write_b128 v183, v[0:3] offset:32768
	s_waitcnt vmcnt(8)
	ds_write_b16 v184, v12 offset:49152
	ds_write_b16_d16_hi v185, v12 offset:49280
	ds_write_b16 v186, v13 offset:49408
	ds_write_b16_d16_hi v187, v13 offset:49536
	ds_write_b16 v188, v14 offset:49664
	ds_write_b16_d16_hi v189, v14 offset:49792
	ds_write_b16 v190, v15 offset:49920
	ds_write_b16_d16_hi v191, v15 offset:50048
	s_waitcnt lgkmcnt(0)
	s_barrier
	v_mfma_f32_32x32x16_bf16 a[48:63], v[102:105], v[110:113], a[48:63]
	ds_read_b128 v[0:3], v161 offset:0x8000
	ds_read_b128 v[4:7], v161 offset:0x9000
	ds_read_b128 v[8:11], v150 offset:0x8000
	ds_read_b128 v[12:15], v207 offset:0x9000
	ds_read_b128 v[16:19], v39 offset:0x8000
	ds_read_b128 v[20:23], v39 offset:0x9000
	ds_read_b128 v[24:27], v163 offset:0x8000
	v_mfma_f32_32x32x16_bf16 a[48:63], v[118:121], v[126:129], a[48:63]
	ds_read_b128 v[28:31], v224 offset:0x9000
	v_mfma_f32_32x32x16_bf16 a[32:47], v[82:85], v[98:101], 0
	ds_read_b128 v[82:85], v162 offset:0x8000
	v_mfma_f32_32x32x16_bf16 a[16:31], v[86:89], v[94:97], 0
	v_mfma_f32_32x32x16_bf16 a[0:15], v[86:89], v[98:101], 0
	ds_read_b128 v[86:89], v162 offset:0x9000
	ds_read_b128 v[94:97], v151 offset:0x8000
	ds_read_b128 v[98:101], v221 offset:0x9000
	v_mfma_f32_32x32x16_bf16 a[48:63], v[134:137], v[142:145], a[48:63]
	v_mfma_f32_32x32x16_bf16 a[32:47], v[102:105], v[114:117], a[32:47]
	ds_read_b128 v[102:105], v173 offset:0x8000
	v_mfma_f32_32x32x16_bf16 a[16:31], v[106:109], v[110:113], a[16:31]
	v_mfma_f32_32x32x16_bf16 a[0:15], v[106:109], v[114:117], a[0:15]
	ds_read_b128 v[106:109], v173 offset:0x9000
	ds_read_b128 v[110:113], v192 offset:0x8000
	ds_read_b128 v[114:117], v225 offset:0x9000
	s_waitcnt lgkmcnt(12)
	s_waitcnt lgkmcnt(8)
	s_waitcnt lgkmcnt(4)
	s_nop 0
	v_mfma_f32_32x32x16_bf16 a[48:63], v[0:3], v[8:11], a[48:63]
	s_waitcnt lgkmcnt(0)
	s_waitcnt vmcnt(7)
	ds_write_b128 v152, v[40:43]
	s_waitcnt vmcnt(3)
	ds_write_b16 v153, v52 offset:16384
	ds_write_b16_d16_hi v154, v52 offset:16512
	ds_write_b16 v155, v53 offset:16640
	ds_write_b16_d16_hi v156, v53 offset:16768
	ds_write_b16 v157, v54 offset:16896
	ds_write_b16_d16_hi v158, v54 offset:17024
	ds_write_b16 v159, v55 offset:17152
	ds_write_b16_d16_hi v160, v55 offset:17280
	ds_write_b128 v164, v[32:35]
	s_waitcnt vmcnt(2)
	ds_write_b16 v165, v56 offset:16384
	ds_write_b16_d16_hi v166, v56 offset:16512
	ds_write_b16 v167, v57 offset:16640
	ds_write_b16_d16_hi v168, v57 offset:16768
	ds_write_b16 v169, v58 offset:16896
	ds_write_b16_d16_hi v170, v58 offset:17024
	ds_write_b16 v171, v59 offset:17152
	ds_write_b16_d16_hi v172, v59 offset:17280
	ds_write_b128 v174, v[44:47]
	s_waitcnt vmcnt(1)
	ds_write_b16 v175, v60 offset:16384
	ds_write_b16_d16_hi v176, v60 offset:16512
	ds_write_b16 v177, v61 offset:16640
	ds_write_b16_d16_hi v178, v61 offset:16768
	ds_write_b16 v179, v62 offset:16896
	ds_write_b16_d16_hi v180, v62 offset:17024
	ds_write_b16 v181, v63 offset:17152
	ds_write_b16_d16_hi v182, v63 offset:17280
	ds_write_b128 v183, v[48:51]
	s_waitcnt vmcnt(0)
	ds_write_b16 v184, v64 offset:16384
	ds_write_b16_d16_hi v185, v64 offset:16512
	ds_write_b16 v186, v65 offset:16640
	ds_write_b16_d16_hi v187, v65 offset:16768
	ds_write_b16 v188, v66 offset:16896
	ds_write_b16_d16_hi v189, v66 offset:17024
	ds_write_b16 v190, v67 offset:17152
	ds_write_b16_d16_hi v191, v67 offset:17280
	s_waitcnt lgkmcnt(0)
	s_barrier
	v_mfma_f32_32x32x16_bf16 a[32:47], v[118:121], v[130:133], a[32:47]
	v_mfma_f32_32x32x16_bf16 a[48:63], v[16:19], v[24:27], a[48:63]
	v_mfma_f32_32x32x16_bf16 a[16:31], v[122:125], v[126:129], a[16:31]
	v_mfma_f32_32x32x16_bf16 a[0:15], v[122:125], v[130:133], a[0:15]
	v_mfma_f32_32x32x16_bf16 a[32:47], v[134:137], v[146:149], a[32:47]
	v_mfma_f32_32x32x16_bf16 a[48:63], v[82:85], v[94:97], a[48:63]
	v_mfma_f32_32x32x16_bf16 a[16:31], v[138:141], v[142:145], a[16:31]
	v_mfma_f32_32x32x16_bf16 a[0:15], v[138:141], v[146:149], a[0:15]
	v_mfma_f32_32x32x16_bf16 a[32:47], v[0:3], v[12:15], a[32:47]
	v_lshrrev_b32_e32 v1, 3, v37
	v_and_b32_e32 v0, 64, v37
	v_and_b32_e32 v1, 4, v1
	v_or3_b32 v2, v0, v1, s4
	v_or_b32_e32 v0, s5, v36
	v_add_u32_e32 v0, v0, v38
	v_and_b32_e32 v1, 0xdf, v0
	v_mfma_f32_32x32x16_bf16 a[48:63], v[102:105], v[110:113], a[48:63]
	v_ashrrev_i32_e32 v0, 7, v0
	v_and_b32_e32 v3, -2, v0
	v_lshl_add_u32 v2, v2, 6, v3
	v_ashrrev_i32_e32 v3, 31, v2
	v_lshlrev_b32_e32 v192, 1, v1
	v_lshl_add_u64 v[0:1], s[0:1], 0, v[192:193]
	s_mov_b32 s0, 0x10000
	v_mfma_f32_32x32x16_bf16 a[16:31], v[4:7], v[8:11], a[16:31]
	v_mfma_f32_32x32x16_bf16 a[0:15], v[4:7], v[12:15], a[0:15]
	v_lshlrev_b64 v[4:5], 9, v[2:3]
	s_nop 1
	v_accvgpr_read_b32 v3, a48
	v_bfe_u32 v6, v3, 16, 1
	v_lshl_add_u64 v[4:5], v[0:1], 0, v[4:5]
	v_add3_u32 v3, v3, v6, s80
	global_store_short_d16_hi v[4:5], v3, off
	v_accvgpr_read_b32 v3, a49
	v_bfe_u32 v6, v3, 16, 1
	v_add3_u32 v3, v3, v6, s80
	global_store_short_d16_hi v[4:5], v3, off offset:512
	v_accvgpr_read_b32 v3, a50
	v_bfe_u32 v6, v3, 16, 1
	v_add3_u32 v3, v3, v6, s80
	v_add_co_u32_e32 v6, vcc, s0, v4
	v_mfma_f32_32x32x16_bf16 a[32:47], v[16:19], v[28:31], a[32:47]
	s_nop 0
	v_addc_co_u32_e32 v7, vcc, 0, v5, vcc
	global_store_short_d16_hi v[6:7], v3, off
	v_accvgpr_read_b32 v3, a51
	v_bfe_u32 v8, v3, 16, 1
	v_add3_u32 v3, v3, v8, s80
	v_add_u32_e32 v8, 0x200, v2
	global_store_short_d16_hi v[6:7], v3, off offset:512
	v_ashrrev_i32_e32 v9, 31, v8
	v_accvgpr_read_b32 v3, a52
	v_lshlrev_b64 v[8:9], 9, v[8:9]
	v_bfe_u32 v10, v3, 16, 1
	v_lshl_add_u64 v[8:9], v[0:1], 0, v[8:9]
	v_add3_u32 v3, v3, v10, s80
	global_store_short_d16_hi v[8:9], v3, off
	v_accvgpr_read_b32 v3, a53
	v_bfe_u32 v10, v3, 16, 1
	v_add3_u32 v3, v3, v10, s80
	global_store_short_d16_hi v[8:9], v3, off offset:512
	v_accvgpr_read_b32 v3, a54
	v_bfe_u32 v10, v3, 16, 1
	v_add3_u32 v3, v3, v10, s80
	v_add_co_u32_e32 v10, vcc, s0, v8
	v_mfma_f32_32x32x16_bf16 a[32:47], v[82:85], v[98:101], a[32:47]
	s_nop 0
	v_addc_co_u32_e32 v11, vcc, 0, v9, vcc
	global_store_short_d16_hi v[10:11], v3, off
	v_accvgpr_read_b32 v3, a55
	v_bfe_u32 v12, v3, 16, 1
	v_add3_u32 v3, v3, v12, s80
	v_add_u32_e32 v12, 0x400, v2
	global_store_short_d16_hi v[10:11], v3, off offset:512
	v_ashrrev_i32_e32 v13, 31, v12
	v_accvgpr_read_b32 v3, a56
	v_lshlrev_b64 v[12:13], 9, v[12:13]
	v_bfe_u32 v14, v3, 16, 1
	v_lshl_add_u64 v[12:13], v[0:1], 0, v[12:13]
	v_add3_u32 v3, v3, v14, s80
	global_store_short_d16_hi v[12:13], v3, off
	v_accvgpr_read_b32 v3, a57
	v_bfe_u32 v14, v3, 16, 1
	v_add3_u32 v3, v3, v14, s80
	global_store_short_d16_hi v[12:13], v3, off offset:512
	v_accvgpr_read_b32 v3, a58
	v_bfe_u32 v14, v3, 16, 1
	v_add3_u32 v3, v3, v14, s80
	v_add_co_u32_e32 v14, vcc, s0, v12
	v_mfma_f32_32x32x16_bf16 a[32:47], v[102:105], v[114:117], a[32:47]
	s_nop 0
	v_addc_co_u32_e32 v15, vcc, 0, v13, vcc
	global_store_short_d16_hi v[14:15], v3, off
	v_accvgpr_read_b32 v3, a59
	v_bfe_u32 v16, v3, 16, 1
	v_add3_u32 v3, v3, v16, s80
	v_add_u32_e32 v16, 0x600, v2
	global_store_short_d16_hi v[14:15], v3, off offset:512
	v_ashrrev_i32_e32 v17, 31, v16
	v_accvgpr_read_b32 v3, a60
	v_lshlrev_b64 v[16:17], 9, v[16:17]
	v_bfe_u32 v18, v3, 16, 1
	v_lshl_add_u64 v[16:17], v[0:1], 0, v[16:17]
	v_add3_u32 v3, v3, v18, s80
	global_store_short_d16_hi v[16:17], v3, off
	v_accvgpr_read_b32 v3, a61
	v_bfe_u32 v18, v3, 16, 1
	v_add3_u32 v3, v3, v18, s80
	global_store_short_d16_hi v[16:17], v3, off offset:512
	v_accvgpr_read_b32 v3, a62
	v_bfe_u32 v18, v3, 16, 1
	v_add3_u32 v3, v3, v18, s80
	v_add_co_u32_e32 v18, vcc, s0, v16
	v_mfma_f32_32x32x16_bf16 a[16:31], v[20:23], v[24:27], a[16:31]
	s_nop 0
	v_addc_co_u32_e32 v19, vcc, 0, v17, vcc
	global_store_short_d16_hi v[18:19], v3, off
	v_accvgpr_read_b32 v3, a63
	v_mfma_f32_32x32x16_bf16 a[0:15], v[20:23], v[28:31], a[0:15]
	v_bfe_u32 v20, v3, 16, 1
	v_add3_u32 v3, v3, v20, s80
	global_store_short_d16_hi v[18:19], v3, off offset:512
	v_accvgpr_read_b32 v3, a32
	v_bfe_u32 v20, v3, 16, 1
	v_add3_u32 v3, v3, v20, s80
	global_store_short_d16_hi v[4:5], v3, off offset:64
	v_accvgpr_read_b32 v3, a33
	v_bfe_u32 v20, v3, 16, 1
	v_add3_u32 v3, v3, v20, s80
	global_store_short_d16_hi v[4:5], v3, off offset:576
	v_accvgpr_read_b32 v3, a34
	v_bfe_u32 v4, v3, 16, 1
	v_add3_u32 v3, v3, v4, s80
	global_store_short_d16_hi v[6:7], v3, off offset:64
	v_accvgpr_read_b32 v3, a35
	v_bfe_u32 v4, v3, 16, 1
	v_add3_u32 v3, v3, v4, s80
	global_store_short_d16_hi v[6:7], v3, off offset:576
	v_accvgpr_read_b32 v3, a36
	v_bfe_u32 v4, v3, 16, 1
	v_add3_u32 v3, v3, v4, s80
	global_store_short_d16_hi v[8:9], v3, off offset:64
	v_accvgpr_read_b32 v3, a37
	v_bfe_u32 v4, v3, 16, 1
	v_add3_u32 v3, v3, v4, s80
	global_store_short_d16_hi v[8:9], v3, off offset:576
	v_accvgpr_read_b32 v3, a38
	v_bfe_u32 v4, v3, 16, 1
	v_add3_u32 v3, v3, v4, s80
	global_store_short_d16_hi v[10:11], v3, off offset:64
	v_accvgpr_read_b32 v3, a39
	v_bfe_u32 v4, v3, 16, 1
	v_add3_u32 v3, v3, v4, s80
	global_store_short_d16_hi v[10:11], v3, off offset:576
	v_accvgpr_read_b32 v3, a40
	v_bfe_u32 v4, v3, 16, 1
	v_add3_u32 v3, v3, v4, s80
	global_store_short_d16_hi v[12:13], v3, off offset:64
	v_accvgpr_read_b32 v3, a41
	v_bfe_u32 v4, v3, 16, 1
	v_add3_u32 v3, v3, v4, s80
	global_store_short_d16_hi v[12:13], v3, off offset:576
	v_accvgpr_read_b32 v3, a42
	v_bfe_u32 v4, v3, 16, 1
	v_mfma_f32_32x32x16_bf16 a[16:31], v[86:89], v[94:97], a[16:31]
	v_add3_u32 v3, v3, v4, s80
	global_store_short_d16_hi v[14:15], v3, off offset:64
	v_accvgpr_read_b32 v3, a43
	v_bfe_u32 v4, v3, 16, 1
	v_add3_u32 v3, v3, v4, s80
	global_store_short_d16_hi v[14:15], v3, off offset:576
	v_accvgpr_read_b32 v3, a44
	v_bfe_u32 v4, v3, 16, 1
	v_add3_u32 v3, v3, v4, s80
	global_store_short_d16_hi v[16:17], v3, off offset:64
	v_accvgpr_read_b32 v3, a45
	v_mfma_f32_32x32x16_bf16 a[16:31], v[106:109], v[110:113], a[16:31]
	v_bfe_u32 v4, v3, 16, 1
	v_add3_u32 v3, v3, v4, s80
	global_store_short_d16_hi v[16:17], v3, off offset:576
	v_accvgpr_read_b32 v3, a46
	v_bfe_u32 v4, v3, 16, 1
	v_add3_u32 v3, v3, v4, s80
	global_store_short_d16_hi v[18:19], v3, off offset:64
	v_accvgpr_read_b32 v3, a47
	v_bfe_u32 v4, v3, 16, 1
	v_add3_u32 v3, v3, v4, s80
	v_add_u32_e32 v4, 0x800, v2
	global_store_short_d16_hi v[18:19], v3, off offset:576
	v_ashrrev_i32_e32 v5, 31, v4
	v_accvgpr_read_b32 v3, a16
	v_lshlrev_b64 v[4:5], 9, v[4:5]
	v_bfe_u32 v6, v3, 16, 1
	v_lshl_add_u64 v[4:5], v[0:1], 0, v[4:5]
	v_add3_u32 v3, v3, v6, s80
	global_store_short_d16_hi v[4:5], v3, off
	v_accvgpr_read_b32 v3, a17
	v_bfe_u32 v6, v3, 16, 1
	v_add3_u32 v3, v3, v6, s80
	global_store_short_d16_hi v[4:5], v3, off offset:512
	v_accvgpr_read_b32 v3, a18
	v_bfe_u32 v6, v3, 16, 1
	v_add3_u32 v3, v3, v6, s80
	v_add_co_u32_e32 v6, vcc, s0, v4
	v_mfma_f32_32x32x16_bf16 a[0:15], v[86:89], v[98:101], a[0:15]
	s_nop 0
	v_addc_co_u32_e32 v7, vcc, 0, v5, vcc
	global_store_short_d16_hi v[6:7], v3, off
	v_accvgpr_read_b32 v3, a19
	v_bfe_u32 v8, v3, 16, 1
	v_add3_u32 v3, v3, v8, s80
	v_add_u32_e32 v8, 0xa00, v2
	global_store_short_d16_hi v[6:7], v3, off offset:512
	v_ashrrev_i32_e32 v9, 31, v8
	v_accvgpr_read_b32 v3, a20
	v_lshlrev_b64 v[8:9], 9, v[8:9]
	v_bfe_u32 v10, v3, 16, 1
	v_lshl_add_u64 v[8:9], v[0:1], 0, v[8:9]
	v_add3_u32 v3, v3, v10, s80
	global_store_short_d16_hi v[8:9], v3, off
	v_accvgpr_read_b32 v3, a21
	v_bfe_u32 v10, v3, 16, 1
	v_add3_u32 v3, v3, v10, s80
	global_store_short_d16_hi v[8:9], v3, off offset:512
	v_accvgpr_read_b32 v3, a22
	v_bfe_u32 v10, v3, 16, 1
	v_add3_u32 v3, v3, v10, s80
	v_add_co_u32_e32 v10, vcc, s0, v8
	v_mfma_f32_32x32x16_bf16 a[0:15], v[106:109], v[114:117], a[0:15]
	s_nop 0
	v_addc_co_u32_e32 v11, vcc, 0, v9, vcc
	global_store_short_d16_hi v[10:11], v3, off
	v_accvgpr_read_b32 v3, a23
	v_bfe_u32 v12, v3, 16, 1
	v_add3_u32 v3, v3, v12, s80
	v_add_u32_e32 v12, 0xc00, v2
	global_store_short_d16_hi v[10:11], v3, off offset:512
	v_ashrrev_i32_e32 v13, 31, v12
	v_accvgpr_read_b32 v3, a24
	v_lshlrev_b64 v[12:13], 9, v[12:13]
	v_bfe_u32 v14, v3, 16, 1
	v_lshl_add_u64 v[12:13], v[0:1], 0, v[12:13]
	v_add3_u32 v3, v3, v14, s80
	global_store_short_d16_hi v[12:13], v3, off
	v_accvgpr_read_b32 v3, a25
	v_bfe_u32 v14, v3, 16, 1
	v_add3_u32 v3, v3, v14, s80
	global_store_short_d16_hi v[12:13], v3, off offset:512
	v_accvgpr_read_b32 v3, a26
	v_bfe_u32 v14, v3, 16, 1
	v_add3_u32 v3, v3, v14, s80
	v_add_co_u32_e32 v14, vcc, s0, v12
	v_add_u32_e32 v2, 0xe00, v2
	s_nop 0
	v_addc_co_u32_e32 v15, vcc, 0, v13, vcc
	global_store_short_d16_hi v[14:15], v3, off
	v_accvgpr_read_b32 v3, a27
	v_bfe_u32 v16, v3, 16, 1
	v_add3_u32 v3, v3, v16, s80
	global_store_short_d16_hi v[14:15], v3, off offset:512
	v_ashrrev_i32_e32 v3, 31, v2
	v_lshlrev_b64 v[2:3], 9, v[2:3]
	v_lshl_add_u64 v[0:1], v[0:1], 0, v[2:3]
	v_accvgpr_read_b32 v2, a28
	v_bfe_u32 v3, v2, 16, 1
	v_add3_u32 v2, v2, v3, s80
	global_store_short_d16_hi v[0:1], v2, off
	v_accvgpr_read_b32 v2, a29
	v_bfe_u32 v3, v2, 16, 1
	v_add3_u32 v2, v2, v3, s80
	global_store_short_d16_hi v[0:1], v2, off offset:512
	v_accvgpr_read_b32 v2, a30
	v_bfe_u32 v3, v2, 16, 1
	v_add3_u32 v16, v2, v3, s80
	v_add_co_u32_e32 v2, vcc, s0, v0
	s_nop 1
	v_addc_co_u32_e32 v3, vcc, 0, v1, vcc
	global_store_short_d16_hi v[2:3], v16, off
	v_accvgpr_read_b32 v16, a31
	v_bfe_u32 v17, v16, 16, 1
	v_add3_u32 v16, v16, v17, s80
	global_store_short_d16_hi v[2:3], v16, off offset:512
	v_accvgpr_read_b32 v16, a0
	v_bfe_u32 v17, v16, 16, 1
	v_add3_u32 v16, v16, v17, s80
	global_store_short_d16_hi v[4:5], v16, off offset:64
	v_accvgpr_read_b32 v16, a1
	v_bfe_u32 v17, v16, 16, 1
	v_add3_u32 v16, v16, v17, s80
	global_store_short_d16_hi v[4:5], v16, off offset:576
	v_accvgpr_read_b32 v4, a2
	v_bfe_u32 v5, v4, 16, 1
	v_add3_u32 v4, v4, v5, s80
	global_store_short_d16_hi v[6:7], v4, off offset:64
	v_accvgpr_read_b32 v4, a3
	v_bfe_u32 v5, v4, 16, 1
	v_add3_u32 v4, v4, v5, s80
	global_store_short_d16_hi v[6:7], v4, off offset:576
	v_accvgpr_read_b32 v4, a4
	v_bfe_u32 v5, v4, 16, 1
	v_add3_u32 v4, v4, v5, s80
	global_store_short_d16_hi v[8:9], v4, off offset:64
	v_accvgpr_read_b32 v4, a5
	v_bfe_u32 v5, v4, 16, 1
	v_add3_u32 v4, v4, v5, s80
	global_store_short_d16_hi v[8:9], v4, off offset:576
	v_accvgpr_read_b32 v4, a6
	v_bfe_u32 v5, v4, 16, 1
	v_add3_u32 v4, v4, v5, s80
	global_store_short_d16_hi v[10:11], v4, off offset:64
	v_accvgpr_read_b32 v4, a7
	v_bfe_u32 v5, v4, 16, 1
	v_add3_u32 v4, v4, v5, s80
	global_store_short_d16_hi v[10:11], v4, off offset:576
	v_accvgpr_read_b32 v4, a8
	v_bfe_u32 v5, v4, 16, 1
	v_add3_u32 v4, v4, v5, s80
	global_store_short_d16_hi v[12:13], v4, off offset:64
	v_accvgpr_read_b32 v4, a9
	v_bfe_u32 v5, v4, 16, 1
	v_add3_u32 v4, v4, v5, s80
	global_store_short_d16_hi v[12:13], v4, off offset:576
	v_accvgpr_read_b32 v4, a10
	v_bfe_u32 v5, v4, 16, 1
	v_add3_u32 v4, v4, v5, s80
	global_store_short_d16_hi v[14:15], v4, off offset:64
	v_accvgpr_read_b32 v4, a11
	v_bfe_u32 v5, v4, 16, 1
	v_add3_u32 v4, v4, v5, s80
	global_store_short_d16_hi v[14:15], v4, off offset:576
	v_accvgpr_read_b32 v4, a12
	v_bfe_u32 v5, v4, 16, 1
	v_add3_u32 v4, v4, v5, s80
	global_store_short_d16_hi v[0:1], v4, off offset:64
	v_accvgpr_read_b32 v4, a13
	v_bfe_u32 v5, v4, 16, 1
	v_add3_u32 v4, v4, v5, s80
	global_store_short_d16_hi v[0:1], v4, off offset:576
	v_accvgpr_read_b32 v0, a14
	v_bfe_u32 v1, v0, 16, 1
	v_add3_u32 v0, v0, v1, s80
	global_store_short_d16_hi v[2:3], v0, off offset:64
	v_accvgpr_read_b32 v0, a15
	v_bfe_u32 v1, v0, 16, 1
	v_add3_u32 v0, v0, v1, s80
	global_store_short_d16_hi v[2:3], v0, off offset:576
